# rowwise tiles remapped to the GEMM owner group; 3 grid barriers closed per XCC when the runtime placement check passes (else global)
# speedup vs baseline: 1.1171x; 1.1171x over previous
; #define LAS __attribute__((address_space(3)))
; __device__ __forceinline__ unsigned xb_add(unsigned* p, unsigned v) { return __hip_atomic_fetch_add(p, v, __ATOMIC_RELAXED, __HIP_MEMORY_SCOPE_AGENT); }
; __device__ __forceinline__ unsigned xb_xcc_id() { return (unsigned)__builtin_amdgcn_s_getreg((3 << 11) | 20) & 0xFu; }
; #define LAS __attribute__((address_space(3)))
; __device__ __forceinline__ XcdBarrier xcd_barrier_post(unsigned* bar, volatile LAS unsigned* st) {
;     XcdBarrier b; b.bar = bar; b.x = xb_xcc_id(); b.st = st;
;     if (threadIdx.x == 0) (void)xb_add(&bar[XB_XCNT(b.x)], 1u);
;     return b;
; __global__ void __launch_bounds__(512, 2) fwd_kernel(Args a) {
;     ...
;     if (threadIdx.x == 0) { MISC[0] = 0u; MISC[1] = 0u; }
;     __syncthreads();
;     XcdBarrier bar = xcd_barrier_post((unsigned*)ws, MISC);
.LBB0_2:
	s_or_b64 exec, exec, s[4:5]
	s_waitcnt lgkmcnt(0)
	s_barrier
	s_getreg_b32 s3, hwreg(HW_REG_XCC_ID, 0, 4)
	s_and_b32 s33, s3, 15
	s_and_saveexec_b64 s[4:5], s[10:11]
	s_cbranch_execz .LBB0_5
	s_mov_b64 s[6:7], exec
	v_mbcnt_lo_u32_b32 v1, s6, 0
	v_mbcnt_hi_u32_b32 v1, s7, v1
	v_cmp_eq_u32_e32 vcc, 0, v1
	s_and_b64 s[8:9], exec, vcc
	s_mov_b64 exec, s[8:9]
	s_cbranch_execz .LBB0_5
	s_lshl_b32 s3, s33, 8
	s_bcnt1_i32_b64 s6, s[6:7]
	v_mov_b32_e32 v1, s3
	v_mov_b32_e32 v2, s6
	global_atomic_add v1, v2, s[94:95] offset:1024
	s_sub_u32 s3, s33, s2
	s_and_b32 s3, s3, 7
	s_lshl_b32 s3, 1, s3
	s_lshl_b32 s6, s33, 13
	s_and_b32 s6, s6, 0x10000
	s_or_b32 s3, s3, s6
	v_mov_b32_e32 v1, 0
	v_mov_b32_e32 v2, s3
	global_atomic_or v1, v2, s[94:95] offset:768

; #define LAS __attribute__((address_space(3)))
; #define LAS __attribute__((address_space(3)))
; __device__ __forceinline__ void rowwise_phase(const Args& a, LAS unsigned char* lds, bool from_partials, bool has_y, bool has_h, bool xin_bf, int xout_mode, ...
;     int tid_ = threadIdx.x; asm volatile("" : "+v"(tid_)); const int tid = tid_, lane = tid & 63, wave = tid >> 6;
;     LAS float* vec = (LAS float*)lds;
;     for (int tile = blockIdx.x; tile < T / 256; tile += gridDim.x) {
;         const int b = tile / (SEQ / 256);
;         __syncthreads();
;         for (int col = tid; col < DM; col += 512) {
;             if (from_partials) {
;                 if (has_y) vec[col] = mod_val(a, l_y, b, gate_idx, col) * g_post[col];
;                 if (has_h) { vec[DM + col] = g_pre[col] * (1.0f + mod_val(a, l_h, b, scale_idx, col)); vec[2 * DM + col] = mod_val(a, l_h, b, shift_idx, col); }
;             } else {
;                 if (has_y) vec[col] = mod_fin(a, l_y, b, gate_idx, col) * g_post[col];
;                 if (has_h) { vec[DM + col] = g_pre[col] * (1.0f + mod_fin(a, l_h, b, scale_idx, col)); vec[2 * DM + col] = mod_fin(a, l_h, b, shift_idx, col); }
;             }
;         }
;         __syncthreads();
; #pragma unroll 1
;         for (int r = wave * 4; r < 256; r += 32) {
.LBB0_100:
	s_or_b64 exec, exec, s[0:1]
	v_readlane_b32 s0, v246, 7
	v_readlane_b32 s1, v246, 8
	v_mov_b32_e32 v40, v192
	s_and_b64 vcc, exec, s[0:1]
	v_mbcnt_lo_u32_b32 v56, -1, 0
	s_waitcnt lgkmcnt(0)
	s_barrier
	v_mov_b32_e32 v247, 0
	global_load_dword v247, v247, s[94:95] offset:768 sc1
	s_waitcnt vmcnt(0)
	v_bcnt_u32_b32 v247, v247, 0
	v_cmp_eq_u32_e64 s[100:101], 1, v247
	s_nop 1
	s_cmp_eq_u32 s96, 0x100
	s_cselect_b64 s[100:101], s[100:101], 0
	v_cndmask_b32_e64 v247, 0, 1, s[100:101]
	v_writelane_b32 v245, s48, 24
	s_cbranch_vccz .LBB0_117
	v_lshlrev_b32_e32 v1, 5, v40
	v_and_b32_e32 v1, 0x7e0, v1
	v_add_u32_e32 v57, 0, v1
	v_max_i32_e32 v1, 0x200, v40
	v_sub_u32_e32 v1, v1, v40
	s_movk_i32 s0, 0x400
	v_ashrrev_i32_e32 v0, 4, v40
	v_add_u32_e32 v1, 0x1ff, v1
	v_lshlrev_b32_e32 v58, 2, v40
	v_cmp_gt_i32_e64 s[36:37], s0, v40
	v_and_b32_e32 v0, -4, v0
	s_movk_i32 s0, 0x100
	v_lshrrev_b32_e32 v2, 9, v1
	v_add_u32_e32 v3, 0, v58
	v_cmp_gt_i32_e64 s[38:39], s0, v0
	v_add_u32_e32 v5, 1, v2
	s_movk_i32 s0, 0x5ff
	v_lshl_add_u32 v2, v2, 11, v3
	v_add_u32_e32 v59, 0x1000, v3
	v_add_u32_e32 v4, 0x2000, v3
	v_cmp_lt_u32_e32 vcc, s0, v1
	v_add_u32_e32 v3, 0x1000, v2
	v_cmp_gt_u32_e64 s[40:41], 2.0, v1
	v_add_u32_e32 v1, 0x2000, v2
	v_cmp_lt_u32_e64 s[0:1], v3, v59
	v_cmp_lt_u32_e64 s[42:43], v1, v4
	s_or_b64 s[0:1], s[42:43], s[0:1]
	v_ashrrev_i32_e32 v1, 31, v0
	s_xor_b64 s[0:1], s[0:1], -1
	v_subrev_u32_e32 v62, 32, v0
	v_lshlrev_b64 v[2:3], 12, v[0:1]
	v_and_b32_e32 v4, 63, v40
	v_lshlrev_b64 v[0:1], 11, v[0:1]
	s_and_b64 s[0:1], s[0:1], s[40:41]
	v_lshl_or_b32 v0, v4, 4, v0
	v_and_b32_e32 v60, 0xfffffe, v5
	s_and_b64 s[14:15], vcc, s[0:1]
	v_lshl_or_b32 v2, v4, 5, v2
	v_lshl_add_u64 v[0:1], s[94:95], 0, v[0:1]
	s_mov_b64 s[0:1], 0x32000000
	s_movk_i32 s4, 0x1000
	v_lshl_add_u32 v61, v60, 9, v40
	v_add_u32_e32 v41, 0x200, v40
	v_cmp_ne_u32_e64 s[40:41], v5, v60
	v_lshl_add_u64 v[42:43], s[56:57], 0, v[2:3]
	v_lshl_add_u64 v[44:45], v[0:1], 0, s[0:1]
	s_mov_b32 s5, 0x30000
	s_mov_b32 s30, 0x60000
	s_mov_b32 s31, 0x90000
	s_mov_b32 s34, 0xc0000
	s_mov_b32 s35, 0xf0000
	s_mov_b32 s42, 0x120000
	s_mov_b32 s43, 0x150000
	s_mov_b32 s44, 0x180000
	s_mov_b32 s45, 0x1b0000
	s_mov_b32 s46, 0x1e0000
	s_mov_b32 s47, 0x210000
	s_mov_b32 s48, 0x240000
	s_mov_b32 s49, 0x270000
	s_mov_b32 s50, 0x2a0000
	s_mov_b32 s51, 0x2d0000
	s_mov_b32 s52, 0x300000
	s_mov_b32 s53, 0x330000
	s_mov_b32 s54, 0x360000
	s_mov_b32 s55, 0x390000
	s_mov_b32 s56, 0x3c0000
	s_mov_b32 s57, 0x3f0000
	s_mov_b32 s58, 0x420000
	s_mov_b32 s59, 0x450000
	s_mov_b32 s60, 0x480000
	s_mov_b32 s61, 0x4b0000
	s_mov_b32 s62, 0x4e0000
	s_mov_b32 s63, 0x510000
	s_mov_b32 s64, 0x540000
	s_mov_b32 s65, 0x570000
	s_mov_b32 s66, 0x5a0000
	s_mov_b32 s67, 0x5d0000
	v_mov_b32_e32 v63, 0x358637bd
	v_mbcnt_hi_u32_b32 v64, -1, v56
	s_and_b32 s100, s2, 7
	s_lshl_b32 s100, s100, 5
	s_lshr_b32 s101, s2, 3
	s_or_b32 s100, s100, s101
	s_cmp_eq_u32 s96, 0x100
	s_cselect_b32 s18, s100, s2
	s_branch .LBB0_103

; __device__ __forceinline__ unsigned xb_ld(unsigned* p)              { return __hip_atomic_load(p, __ATOMIC_RELAXED, __HIP_MEMORY_SCOPE_AGENT); }
; __device__ __forceinline__ unsigned xb_add(unsigned* p, unsigned v) { return __hip_atomic_fetch_add(p, v, __ATOMIC_RELAXED, __HIP_MEMORY_SCOPE_AGENT); }
; #define XB_SPIN(cond, bar) do { unsigned _sp = 0; while (cond) { __builtin_amdgcn_s_sleep(1); \
;     if ((++_sp & 255u) == 0u) { if (xb_ld(&(bar)[XB_TMO])) break; if (_sp > XB_SPIN_CAP) { atomicAdd(&(bar)[XB_TMO], 1u); break; } } } } while (0)
; __device__ __forceinline__ void xcd_barrier(const XcdBarrier& b) {
;     ...
;     if (threadIdx.x == 0) {
;         unsigned* bar = b.bar;
;         __builtin_amdgcn_s_waitcnt(0);
;         unsigned nloc = b.st[0], nx = b.st[1];
;         if (nloc == 0u) { xcd_barrier_complete(bar, b.x, nloc, nx); b.st[0] = nloc; b.st[1] = nx; }
;         const unsigned old = xb_add(&bar[XB_XSUB(b.x)], 1u);
;         const unsigned gen = old / nloc;
;         if (old + 1u == (gen + 1u) * nloc) {
;             __builtin_amdgcn_fence(__ATOMIC_RELEASE, "agent");
;             asm volatile("s_waitcnt vmcnt(0)" ::: "memory");
;             const unsigned og = xb_add(&bar[XB_TOP], 1u);
;             const unsigned tg = og / nx;
;             if (og + 1u == (tg + 1u) * nx) xb_add(&bar[XB_TOPGEN], 1u);
;             else XB_SPIN(xb_ld(&bar[XB_TOPGEN]) == tg, bar);
;             __builtin_amdgcn_fence(__ATOMIC_ACQUIRE, "agent");
;             xb_add(&bar[XB_XGEN(b.x)], 1u);
;             asm volatile("s_waitcnt vmcnt(0)" ::: "memory");
.LBB0_153:
	s_andn2_saveexec_b64 s[4:5], s[8:9]
	s_cbranch_execz .LBB0_173
	v_readfirstlane_b32 s100, v247
	s_nop 3
	s_cmp_eq_u32 s100, 0
	s_cbranch_scc1 .Lxb_global_0
	v_readlane_b32 s100, v245, 18
	v_readlane_b32 s101, v245, 19
	v_mov_b32_e32 v251, 0
	v_mov_b32_e32 v250, 1
	s_nop 4
	global_atomic_add v251, v250, s[100:101]
	s_waitcnt vmcnt(1)
	s_branch .LBB0_173
.Lxb_global_0:
	s_mov_b64 s[8:9], exec
	buffer_wbl2 sc1
	s_waitcnt lgkmcnt(0)
	s_waitcnt vmcnt(0)
	v_mbcnt_lo_u32_b32 v1, s8, 0
	v_mbcnt_hi_u32_b32 v1, s9, v1
	v_cmp_eq_u32_e32 vcc, 0, v1
	s_and_saveexec_b64 s[14:15], vcc
	s_cbranch_execz .LBB0_156
	s_bcnt1_i32_b64 s3, s[8:9]
	v_readlane_b32 s4, v245, 20
	v_mov_b32_e32 v2, 0
	v_mov_b32_e32 v3, s3
	v_readlane_b32 s5, v245, 21
	s_nop 4
	global_atomic_add v2, v2, v3, s[4:5] sc0

; #define LAS __attribute__((address_space(3)))
; #define LAS __attribute__((address_space(3)))
; __device__ __forceinline__ void rowwise_phase(const Args& a, LAS unsigned char* lds, bool from_partials, bool has_y, bool has_h, bool xin_bf, int xout_mode, ...
;     int tid_ = threadIdx.x; asm volatile("" : "+v"(tid_)); const int tid = tid_, lane = tid & 63, wave = tid >> 6;
;     LAS float* vec = (LAS float*)lds;
;     for (int tile = blockIdx.x; tile < T / 256; tile += gridDim.x) {
;         const int b = tile / (SEQ / 256);
;         __syncthreads();
;         for (int col = tid; col < DM; col += 512) {
;             if (from_partials) {
;                 if (has_y) vec[col] = mod_val(a, l_y, b, gate_idx, col) * g_post[col];
;                 if (has_h) { vec[DM + col] = g_pre[col] * (1.0f + mod_val(a, l_h, b, scale_idx, col)); vec[2 * DM + col] = mod_val(a, l_h, b, shift_idx, col); }
;             } else {
;                 if (has_y) vec[col] = mod_fin(a, l_y, b, gate_idx, col) * g_post[col];
;                 if (has_h) { vec[DM + col] = g_pre[col] * (1.0f + mod_fin(a, l_h, b, scale_idx, col)); vec[2 * DM + col] = mod_fin(a, l_h, b, shift_idx, col); }
;             }
;         }
;         __syncthreads();
; #pragma unroll 1
;         for (int r = wave * 4; r < 256; r += 32) {
.LBB0_502:
	s_or_b64 exec, exec, s[0:1]
	v_readlane_b32 s0, v246, 7
	v_readlane_b32 s1, v246, 8
	s_waitcnt lgkmcnt(0)
	v_mov_b32_e32 v2, v192
	s_andn2_b64 vcc, exec, s[0:1]
	v_cndmask_b32_e64 v0, 0, 1, s[0:1]
	v_cmp_ne_u32_e64 s[38:39], 1, v0
	s_barrier
	s_cbranch_vccnz .LBB0_519
	v_readlane_b32 s40, v246, 11
	v_readlane_b32 s0, v244, 21
	v_readlane_b32 s48, v246, 19
	v_readlane_b32 s49, v246, 20
	v_readlane_b32 s50, v246, 21
	v_readlane_b32 s51, v246, 22
	v_readlane_b32 s52, v246, 23
	v_readlane_b32 s53, v246, 24
	v_readlane_b32 s1, v244, 22
	s_lshl_b32 s76, s0, 10
	v_readlane_b32 s54, v246, 25
	v_readlane_b32 s55, v246, 26
	s_mov_b64 s[48:49], s[52:53]
	s_lshl_b64 s[0:1], s[76:77], 2
	s_mov_b64 s[50:51], s[54:55]
	v_ashrrev_i32_e32 v3, 4, v2
	s_add_u32 s48, s50, s0
	v_and_b32_e32 v6, -4, v3
	v_max_i32_e32 v3, 0x200, v2
	s_addc_u32 s49, s51, s1
	v_sub_u32_e32 v3, v3, v2
	v_readlane_b32 s41, v246, 12
	s_add_u32 s50, s88, s0
	s_movk_i32 s0, 0x400
	v_add_u32_e32 v3, 0x1ff, v3
	v_lshlrev_b32_e32 v12, 2, v2
	v_readlane_b32 s42, v246, 13
	v_readlane_b32 s43, v246, 14
	v_cmp_gt_i32_e64 s[40:41], s0, v2
	s_movk_i32 s0, 0x100
	v_lshrrev_b32_e32 v4, 9, v3
	v_add_u32_e32 v13, 0, v12
	v_readlane_b32 s44, v246, 15
	v_readlane_b32 s45, v246, 16
	v_cmp_gt_i32_e64 s[42:43], s0, v6
	v_add_u32_e32 v9, 1, v4
	s_movk_i32 s0, 0x2dff
	v_lshl_add_u32 v4, v4, 11, v13
	v_readlane_b32 s46, v246, 17
	v_readlane_b32 s47, v246, 18
	v_add_u32_e32 v5, 0x1000, v13
	v_add_u32_e32 v7, 0x2000, v13
	v_cmp_lt_u32_e32 vcc, s0, v3
	v_add_u32_e32 v10, 0x1000, v4
	v_cmp_gt_u32_e64 s[44:45], 2.0, v3
	v_add_u32_e32 v3, 0x2000, v4
	s_addc_u32 s51, s89, s1
	v_cmp_lt_u32_e64 s[0:1], v10, v5
	v_cmp_lt_u32_e64 s[46:47], v3, v7
	s_or_b64 s[0:1], s[46:47], s[0:1]
	v_and_b32_e32 v0, 63, v2
	s_xor_b64 s[0:1], s[0:1], -1
	v_lshlrev_b32_e32 v8, 5, v0
	s_and_b64 s[0:1], s[0:1], s[44:45]
	v_and_b32_e32 v14, 0xfffffe, v9
	v_lshlrev_b32_e32 v0, 4, v0
	v_ashrrev_i32_e32 v7, 31, v6
	v_lshl_add_u32 v15, v14, 9, v2
	v_add_u32_e32 v3, 0x200, v2
	v_cmp_ne_u32_e64 s[44:45], v9, v14
	s_and_b64 s[0:1], vcc, s[0:1]
	v_subrev_u32_e32 v16, 32, v6
	v_lshl_add_u64 v[4:5], s[94:95], 0, v[0:1]
	v_lshlrev_b64 v[6:7], 11, v[6:7]
	v_add_u32_e32 v0, 0, v8
	s_and_b32 s100, s2, 7
	s_lshl_b32 s100, s100, 5
	s_lshr_b32 s101, s2, 3
	s_or_b32 s100, s100, s101
	s_cmp_eq_u32 s96, 0x100
	s_cselect_b32 s46, s100, s2
	v_readlane_b32 s64, v245, 42
	v_readlane_b32 s65, v245, 43
	s_branch .LBB0_505

; __device__ __forceinline__ unsigned xb_ld(unsigned* p)              { return __hip_atomic_load(p, __ATOMIC_RELAXED, __HIP_MEMORY_SCOPE_AGENT); }
; __device__ __forceinline__ unsigned xb_add(unsigned* p, unsigned v) { return __hip_atomic_fetch_add(p, v, __ATOMIC_RELAXED, __HIP_MEMORY_SCOPE_AGENT); }
; #define XB_SPIN(cond, bar) do { unsigned _sp = 0; while (cond) { __builtin_amdgcn_s_sleep(1); \
;     if ((++_sp & 255u) == 0u) { if (xb_ld(&(bar)[XB_TMO])) break; if (_sp > XB_SPIN_CAP) { atomicAdd(&(bar)[XB_TMO], 1u); break; } } } } while (0)
; __device__ __forceinline__ void xcd_barrier(const XcdBarrier& b) {
;     ...
;     if (threadIdx.x == 0) {
;         unsigned* bar = b.bar;
;         __builtin_amdgcn_s_waitcnt(0);
;         unsigned nloc = b.st[0], nx = b.st[1];
;         if (nloc == 0u) { xcd_barrier_complete(bar, b.x, nloc, nx); b.st[0] = nloc; b.st[1] = nx; }
;         const unsigned old = xb_add(&bar[XB_XSUB(b.x)], 1u);
;         const unsigned gen = old / nloc;
;         if (old + 1u == (gen + 1u) * nloc) {
;             __builtin_amdgcn_fence(__ATOMIC_RELEASE, "agent");
;             asm volatile("s_waitcnt vmcnt(0)" ::: "memory");
;             const unsigned og = xb_add(&bar[XB_TOP], 1u);
;             const unsigned tg = og / nx;
;             if (og + 1u == (tg + 1u) * nx) xb_add(&bar[XB_TOPGEN], 1u);
;             else XB_SPIN(xb_ld(&bar[XB_TOPGEN]) == tg, bar);
;             __builtin_amdgcn_fence(__ATOMIC_ACQUIRE, "agent");
;             xb_add(&bar[XB_XGEN(b.x)], 1u);
;             asm volatile("s_waitcnt vmcnt(0)" ::: "memory");
.LBB0_551:
	s_andn2_saveexec_b64 s[16:17], s[36:37]
	s_cbranch_execz .LBB0_571
	v_readfirstlane_b32 s100, v247
	s_nop 3
	s_cmp_eq_u32 s100, 0
	s_cbranch_scc1 .Lxb_global_1
	v_readlane_b32 s100, v245, 18
	v_readlane_b32 s101, v245, 19
	v_mov_b32_e32 v251, 0
	v_mov_b32_e32 v250, 1
	s_nop 4
	global_atomic_add v251, v250, s[100:101]
	s_waitcnt vmcnt(1)
	s_branch .LBB0_571
.Lxb_global_1:
	s_mov_b64 s[16:17], exec
	buffer_wbl2 sc1
	s_waitcnt lgkmcnt(0)
	s_waitcnt vmcnt(0)
	v_mbcnt_lo_u32_b32 v0, s16, 0
	v_mbcnt_hi_u32_b32 v0, s17, v0
	v_cmp_eq_u32_e32 vcc, 0, v0
	s_and_saveexec_b64 s[36:37], vcc
	s_cbranch_execz .LBB0_554
	s_bcnt1_i32_b64 s16, s[16:17]
	v_mov_b32_e32 v3, s16
	v_readlane_b32 s16, v245, 20
	v_readlane_b32 s17, v245, 21
	s_nop 4
	global_atomic_add v3, v1, v3, s[16:17] sc0

; __device__ __forceinline__ void rowwise_phase(const Args& a, LAS unsigned char* lds, bool from_partials, bool has_y, bool has_h, bool xin_bf, int xout_mode, ...
;     ...
;     for (int tile = blockIdx.x; tile < T / 256; tile += gridDim.x) {
;         const int b = tile / (SEQ / 256);
;         __syncthreads();
;         for (int col = tid; col < DM; col += 512) {
;             if (from_partials) {
;                 if (has_y) vec[col] = mod_val(a, l_y, b, gate_idx, col) * g_post[col];
;                 if (has_h) { vec[DM + col] = g_pre[col] * (1.0f + mod_val(a, l_h, b, scale_idx, col)); vec[2 * DM + col] = mod_val(a, l_h, b, shift_idx, col); }
;             } else {
;                 if (has_y) vec[col] = mod_fin(a, l_y, b, gate_idx, col) * g_post[col];
;                 if (has_h) { vec[DM + col] = g_pre[col] * (1.0f + mod_fin(a, l_h, b, scale_idx, col)); vec[2 * DM + col] = mod_fin(a, l_h, b, shift_idx, col); }
;             }
;         }
;         __syncthreads();
; __global__ void __launch_bounds__(512, 2) fwd_kernel(Args a) {
;     ...
;         for (int rep = 0; rep < REP_R; ++rep) rowwise_phase(a, lds, false, true, more, true, more ? 2 : 1, XA, MIX, a.out, XB, H, l, 5, a.g_post_ffn + l * DM, l + 1, 0, 1, a.g_pre_mix + (more ? (l + 1) * DM : 0));
.LBB0_717:
	s_and_b64 s[0:1], s[18:19], exec
	s_movk_i32 s0, 0x400
	v_ashrrev_i32_e32 v3, 4, v2
	v_cmp_gt_i32_e64 s[36:37], s0, v2
	v_and_b32_e32 v4, -4, v3
	s_movk_i32 s0, 0x100
	v_readlane_b32 s40, v244, 21
	v_cmp_gt_i32_e64 s[38:39], s0, v4
	s_mul_i32 s0, s40, 0x30000
	v_readlane_b32 s17, v244, 15
	s_cselect_b32 s16, 0x1000, 0
	v_readlane_b32 s41, v244, 22
	s_mul_hi_u32 s1, s40, 0x30000
	v_ashrrev_i32_e32 v3, 31, v2
	s_add_u32 s0, s17, s0
	v_readlane_b32 s17, v244, 16
	v_and_b32_e32 v0, 63, v2
	v_add_u32_e32 v135, 0xfffffe00, v2
	v_lshl_add_u32 v136, v2, 2, 0
	s_mov_b32 s41, s77
	v_lshlrev_b64 v[2:3], 2, v[2:3]
	s_addc_u32 s1, s17, s1
	v_lshl_add_u64 v[74:75], s[0:1], 0, v[2:3]
	s_lshl_b64 s[0:1], s[40:41], 12
	v_readlane_b32 s40, v246, 11
	s_add_u32 s0, s90, s0
	v_readlane_b32 s48, v246, 19
	v_readlane_b32 s49, v246, 20
	v_readlane_b32 s50, v246, 21
	v_readlane_b32 s51, v246, 22
	v_readlane_b32 s52, v246, 23
	v_readlane_b32 s53, v246, 24
	s_addc_u32 s1, s91, s1
	v_readlane_b32 s54, v246, 25
	v_readlane_b32 s55, v246, 26
	s_mov_b64 s[48:49], s[52:53]
	v_lshl_add_u64 v[76:77], s[0:1], 0, v[2:3]
	s_add_u32 s0, s48, s16
	s_addc_u32 s1, s49, 0
	v_lshl_add_u64 v[78:79], s[0:1], 0, v[2:3]
	v_readlane_b32 s0, v244, 17
	v_readlane_b32 s1, v244, 18
	v_ashrrev_i32_e32 v5, 31, v4
	v_lshlrev_b32_e32 v134, 5, v0
	v_lshl_add_u64 v[80:81], s[0:1], 0, v[2:3]
	v_lshlrev_b64 v[2:3], 12, v[4:5]
	v_or_b32_e32 v2, v2, v134
	v_lshlrev_b32_e32 v0, 4, v0
	v_subrev_u32_e32 v137, 32, v4
	v_lshl_add_u64 v[82:83], s[92:93], 0, v[2:3]
	v_lshl_add_u64 v[84:85], s[94:95], 0, v[0:1]
	v_lshlrev_b64 v[86:87], 11, v[4:5]
	s_and_b32 s100, s2, 7
	s_lshl_b32 s100, s100, 5
	s_lshr_b32 s101, s2, 3
	s_or_b32 s100, s100, s101
	s_sub_u32 s100, 0xff, s100
	s_cmp_eq_u32 s96, 0x100
	s_cselect_b32 s0, s100, s2
	v_readlane_b32 s41, v246, 12
	v_readlane_b32 s42, v246, 13
	v_readlane_b32 s43, v246, 14
	v_readlane_b32 s44, v246, 15
	v_readlane_b32 s45, v246, 16
	v_readlane_b32 s46, v246, 17
	v_readlane_b32 s47, v246, 18
	s_mov_b64 s[50:51], s[54:55]
	s_branch .LBB0_719
